# k3 GLA state-scan work rebalanced across block groups; k1 S5 table assembly moved to the blocks without a 17th GEMM tile
# speedup vs baseline: 1.0041x; 1.0041x over previous
; __device__ __forceinline__ void scans_phase(const int TID, const int BID, const Params& p, const int l, const bool do_gla) {
;     ...
;     if (do_gla) {
;         const bf16_t* ds = (const bf16_t*)(p.ws + WS_DS); const float* dec = (const float*)(p.ws + WS_DECAY); bf16_t* spb = (bf16_t*)(p.ws + WS_SPB);
;         for (int it = 0; ; ++it) {
;             int vb;
;             if (split) { if (BID >= 120) { if (it >= 8) break; vb = (BID - 120) + 136 * it; } else { vb = 1088 + BID + 120 * it; if (vb >= 1280) break; } }
;             else { vb = BID + G * it; if (vb >= 1280) break; }
;             const int e = vb * 512 + TID;
;             const int seq = e >> 16, rem = e & 65535, head = rem >> 14, d = (rem >> 13) & 1, el = rem & 8191, kk = el & 63;
;             const int cb = seq < 2 ? seq * 65 : 130 + (seq - 2) * 33, nc = seq < 2 ? 65 : 33;
.LBB0_675:
	s_add_u32 s2, s94, 0x415a0000
	s_addc_u32 s3, s95, 0
	s_add_u32 s28, s94, 0x50104600
	v_and_b32_e32 v0, 63, v194
	s_addc_u32 s29, s95, 0
	s_sub_i32 s21, 0x3a7, s22
	v_lshlrev_b32_e32 v182, 2, v0
	s_cmpk_lt_i32 s22, 0x78
	v_lshl_add_u64 v[0:1], s[94:95], 0, v[182:183]
	s_mov_b64 s[0:1], 0x47820000
	s_cselect_b64 s[38:39], -1, 0
	s_add_i32 s23, s22, 0xffffff88
	v_lshl_add_u64 v[0:1], v[0:1], 0, s[0:1]
	s_mov_b32 s24, 0
	s_branch .LBB0_678

; __device__ __forceinline__ void scans_phase(const int TID, const int BID, const Params& p, const int l, const bool do_gla) {
;     ...
;         for (int it = 0; ; ++it) {
;             int vb;
;             if (split) { if (BID >= 120) { if (it >= 8) break; vb = (BID - 120) + 136 * it; } else { vb = 1088 + BID + 120 * it; if (vb >= 1280) break; } }
;             else { vb = BID + G * it; if (vb >= 1280) break; }
;             const int e = vb * 512 + TID;
.LBB0_683:
	s_andn2_b64 vcc, exec, s[40:41]
	s_cbranch_vccnz .LBB0_686
	s_cmp_lt_u32 s24, 6
	s_cbranch_scc0 .LBB0_686
	s_mul_i32 s0, s24, 0x88
	s_add_i32 s42, s23, s0
	s_mov_b64 s[0:1], -1

; __device__ __forceinline__ void s5_assemble_a(const int TID, const int BID, const Params& p, int l) {
;     const f32x2* pw = (const f32x2*)(p.ws + WS_PW) + l * PWL; const f32x2* bbar = (const f32x2*)(p.ws + WS_BBAR) + l * BBL;
;     float* kmat = (float*)(p.ws + WS_KMAT); bf16_t* pmat = (bf16_t*)(p.ws + WS_PMAT);
;     const float* cre = p.in[10]; const float* cim = p.in[11];
;     const size_t stride = (size_t)gridDim.x * 512;
;     for (size_t idx = (size_t)BID * 512 + TID; idx < (size_t)32 * 2 * 16 * 256; idx += stride) {
;         const int g = (int)(idx >> 13), d = (int)(idx >> 12) & 1, j = (int)(idx >> 8) & 15, c = (int)(idx >> 4) & 15, cp = (int)idx & 15;
;         kmat[idx] = s5_kval(cre, cim, pw, bbar, l, g, d, j, c, cp);
;     }
;     for (size_t idx = (size_t)BID * 512 + TID; idx < (size_t)32 * 256 * 256; idx += stride) {
.LBB0_1300:
	s_cmpk_lg_i32 s96, 0x100
	s_cbranch_scc1 .Lasma_orig
	s_cmp_lt_i32 s22, 75
	s_cbranch_scc1 .LBB0_1309
	s_sub_u32 s56, s22, 75
	s_mov_b32 s57, 0
	s_mov_b64 s[58:59], 0x16a00
	s_mov_b64 s[60:61], 0x2d400
	s_branch .Lasma_go
.Lasma_orig:
	s_mov_b64 s[56:57], s[22:23]
	v_readlane_b32 s58, v254, 51
	v_readlane_b32 s59, v254, 52
	v_readlane_b32 s60, v253, 39
	v_readlane_b32 s61, v253, 40
.Lasma_go:
	v_readlane_b32 s0, v254, 59
	s_lshl_b64 s[2:3], s[56:57], 9
	v_readlane_b32 s1, v254, 60
	v_lshl_add_u64 v[0:1], s[2:3], 0, v[194:195]
	s_mov_b64 s[2:3], 0x40000
	s_lshl_b64 s[0:1], s[0:1], 19
	v_cmp_gt_u64_e32 vcc, s[2:3], v[0:1]
	s_and_saveexec_b64 s[2:3], vcc
	s_cbranch_execz .LBB0_1305
	s_add_u32 s20, s94, 0x4cec1000
	v_lshlrev_b32_e32 v182, 3, v12
	s_addc_u32 s21, s95, 0
	v_lshl_add_u64 v[2:3], s[0:1], 0, v[182:183]
	s_mov_b64 s[28:29], 0
	v_mov_b64_e32 v[4:5], v[0:1]

; __device__ __forceinline__ float s5_kval(const float* cre, const float* cim, const f32x2* pw, const f32x2* bbar, int l, int g, int d, int j, int c, int cp) {
;     const float* cr = cre + (((size_t)(l * 2 + d) * 32 + g) * 16 + c) * 64; const float* ci = cim + (((size_t)(l * 2 + d) * 32 + g) * 16 + c) * 64;
;     const f32x2* pp = pw + ((size_t)(g * 2 + d) * 17 + j) * 64; const f32x2* bb = bbar + ((size_t)(g * 2 + d) * 64) * 16 + cp;
;     float s = 0.f;
; #pragma unroll 16
;     for (int n = 0; n < 64; ++n) { const f32x2 pv = pp[n]; const f32x2 bv = bb[(size_t)n * 16]; const float er = cr[n] * pv.x - ci[n] * pv.y, ei = cr[n] * pv.y + ci[n] * pv.x; s += er * bv.x - ei * bv.y; }
;     return s;
; }
.LBB0_1303:
	v_lshl_add_u64 v[20:21], s[94:95], 0, v[6:7]
	v_add_co_u32_e32 v56, vcc, 0x48221000, v20
	v_lshl_add_u64 v[24:25], s[94:95], 0, v[8:9]
	s_nop 0
	v_addc_co_u32_e32 v57, vcc, 0, v21, vcc
	v_add_co_u32_e32 v58, vcc, 0x48441000, v24
	v_lshl_add_u64 v[36:37], v[18:19], 0, s[38:39]
	s_nop 0
	v_addc_co_u32_e32 v59, vcc, 0, v25, vcc
	v_lshl_add_u64 v[52:53], v[10:11], 0, s[38:39]
	flat_load_dwordx4 v[20:23], v[56:57]
	flat_load_dwordx2 v[60:61], v[58:59]
	global_load_dwordx4 v[24:27], v[36:37], off offset:48
	global_load_dwordx4 v[28:31], v[36:37], off offset:32
	global_load_dwordx4 v[32:35], v[36:37], off offset:16
	s_nop 0
	global_load_dwordx4 v[36:39], v[36:37], off
	s_nop 0
	global_load_dwordx4 v[40:43], v[52:53], off offset:48
	global_load_dwordx4 v[44:47], v[52:53], off offset:32
	global_load_dwordx4 v[48:51], v[52:53], off offset:16
	s_nop 0
	global_load_dwordx4 v[52:55], v[52:53], off
	s_add_u32 s38, s38, 64
	s_mov_b64 s[40:41], 0x800
	s_addc_u32 s39, s39, 0
	v_lshl_add_u64 v[6:7], v[6:7], 0, s[36:37]
	v_lshl_add_u64 v[8:9], v[8:9], 0, s[40:41]
	s_cmpk_lg_i32 s38, 0x100
	s_waitcnt vmcnt(0) lgkmcnt(0)
	v_pk_mul_f32 v[62:63], v[20:21], v[52:53] op_sel:[1,0] op_sel_hi:[0,0]
	v_pk_fma_f32 v[64:65], v[20:21], v[36:37], v[62:63] neg_lo:[0,0,1] neg_hi:[0,0,1]
	v_pk_fma_f32 v[20:21], v[20:21], v[36:37], v[62:63] op_sel_hi:[1,0,1]
	v_pk_mul_f32 v[52:53], v[22:23], v[52:53] op_sel:[1,1] op_sel_hi:[0,1]
	v_mov_b32_e32 v65, v21
	v_pk_mul_f32 v[20:21], v[60:61], v[64:65]
	v_mov_b32_e32 v60, v37
	v_sub_f32_e32 v20, v20, v21
	v_add_f32_e32 v13, v13, v20
	flat_load_dwordx2 v[20:21], v[58:59] offset:128
	v_pk_fma_f32 v[60:61], v[22:23], v[60:61], v[52:53] neg_lo:[0,0,1] neg_hi:[0,0,1]
	v_pk_fma_f32 v[22:23], v[22:23], v[36:37], v[52:53] op_sel:[0,1,0]
	s_nop 0
	v_mov_b32_e32 v61, v23
	s_waitcnt vmcnt(0) lgkmcnt(0)
	v_pk_mul_f32 v[20:21], v[20:21], v[60:61]
	s_nop 0
	v_sub_f32_e32 v20, v20, v21
	v_add_f32_e32 v13, v13, v20
	flat_load_dwordx4 v[20:23], v[56:57] offset:16
	flat_load_dwordx2 v[36:37], v[58:59] offset:256
	s_waitcnt vmcnt(0) lgkmcnt(0)
	v_pk_mul_f32 v[52:53], v[20:21], v[54:55] op_sel:[1,0] op_sel_hi:[0,0]
	v_pk_fma_f32 v[60:61], v[20:21], v[38:39], v[52:53] neg_lo:[0,0,1] neg_hi:[0,0,1]
	v_pk_fma_f32 v[20:21], v[20:21], v[38:39], v[52:53] op_sel_hi:[1,0,1]
	v_mov_b32_e32 v52, v55
	v_mov_b32_e32 v61, v21
	v_pk_mul_f32 v[20:21], v[36:37], v[60:61]
	v_mov_b32_e32 v36, v39
	v_sub_f32_e32 v20, v20, v21
	v_add_f32_e32 v13, v13, v20
	flat_load_dwordx2 v[20:21], v[58:59] offset:384
	v_mov_b32_e32 v38, v39
	v_pk_mul_f32 v[52:53], v[22:23], v[52:53] op_sel:[1,0] op_sel_hi:[0,0]
	v_pk_fma_f32 v[36:37], v[22:23], v[36:37], v[52:53] neg_lo:[0,0,1] neg_hi:[0,0,1]
	v_pk_fma_f32 v[22:23], v[22:23], v[38:39], v[52:53] op_sel_hi:[1,0,1]
	s_nop 0
	v_mov_b32_e32 v37, v23
	s_waitcnt vmcnt(0) lgkmcnt(0)
	v_pk_mul_f32 v[20:21], v[20:21], v[36:37]
	s_nop 0
	v_sub_f32_e32 v20, v20, v21
	v_add_f32_e32 v13, v13, v20
	flat_load_dwordx4 v[20:23], v[56:57] offset:32
	flat_load_dwordx2 v[36:37], v[58:59] offset:512
	s_waitcnt vmcnt(0) lgkmcnt(0)
	v_pk_mul_f32 v[38:39], v[20:21], v[48:49] op_sel:[1,0] op_sel_hi:[0,0]
	v_pk_fma_f32 v[52:53], v[20:21], v[32:33], v[38:39] neg_lo:[0,0,1] neg_hi:[0,0,1]
	v_pk_fma_f32 v[20:21], v[20:21], v[32:33], v[38:39] op_sel_hi:[1,0,1]
	v_pk_mul_f32 v[38:39], v[22:23], v[48:49] op_sel:[1,1] op_sel_hi:[0,1]
	v_mov_b32_e32 v53, v21
	v_pk_mul_f32 v[20:21], v[36:37], v[52:53]
	v_mov_b32_e32 v36, v33
	v_sub_f32_e32 v20, v20, v21
	v_add_f32_e32 v13, v13, v20
	flat_load_dwordx2 v[20:21], v[58:59] offset:640
	v_pk_fma_f32 v[36:37], v[22:23], v[36:37], v[38:39] neg_lo:[0,0,1] neg_hi:[0,0,1]
	v_pk_fma_f32 v[22:23], v[22:23], v[32:33], v[38:39] op_sel:[0,1,0]
	s_nop 0
	v_mov_b32_e32 v37, v23
	s_waitcnt vmcnt(0) lgkmcnt(0)
	v_pk_mul_f32 v[20:21], v[20:21], v[36:37]
	s_nop 0
	v_sub_f32_e32 v20, v20, v21
	v_add_f32_e32 v13, v13, v20
	flat_load_dwordx4 v[20:23], v[56:57] offset:48
	flat_load_dwordx2 v[32:33], v[58:59] offset:768
	s_waitcnt vmcnt(0) lgkmcnt(0)
	v_pk_mul_f32 v[36:37], v[20:21], v[50:51] op_sel:[1,0] op_sel_hi:[0,0]
	v_pk_fma_f32 v[38:39], v[20:21], v[34:35], v[36:37] neg_lo:[0,0,1] neg_hi:[0,0,1]
	v_pk_fma_f32 v[20:21], v[20:21], v[34:35], v[36:37] op_sel_hi:[1,0,1]
	v_mov_b32_e32 v36, v51
	v_mov_b32_e32 v39, v21
	v_pk_mul_f32 v[20:21], v[32:33], v[38:39]
	v_mov_b32_e32 v32, v35
	v_sub_f32_e32 v20, v20, v21
	v_add_f32_e32 v13, v13, v20
	flat_load_dwordx2 v[20:21], v[58:59] offset:896
	v_mov_b32_e32 v34, v35
	v_pk_mul_f32 v[36:37], v[22:23], v[36:37] op_sel:[1,0] op_sel_hi:[0,0]
	v_pk_fma_f32 v[32:33], v[22:23], v[32:33], v[36:37] neg_lo:[0,0,1] neg_hi:[0,0,1]
	v_pk_fma_f32 v[22:23], v[22:23], v[34:35], v[36:37] op_sel_hi:[1,0,1]
	s_nop 0
	v_mov_b32_e32 v33, v23
	s_waitcnt vmcnt(0) lgkmcnt(0)
	v_pk_mul_f32 v[20:21], v[20:21], v[32:33]
	s_nop 0
	v_sub_f32_e32 v20, v20, v21
	v_add_f32_e32 v13, v13, v20
	flat_load_dwordx4 v[20:23], v[56:57] offset:64
	flat_load_dwordx2 v[32:33], v[58:59] offset:1024
	s_waitcnt vmcnt(0) lgkmcnt(0)
; __device__ __forceinline__ bf16_t f2bf(float f) { return (bf16_t)(cvt_pk_bf16(f, 0.f) & 0xffffu); }
; __device__ __forceinline__ float s5_kval(const float* cre, const float* cim, const f32x2* pw, const f32x2* bbar, int l, int g, int d, int j, int c, int cp) {
;     ...
;     for (int n = 0; n < 64; ++n) { const f32x2 pv = pp[n]; const f32x2 bv = bb[(size_t)n * 16]; const float er = cr[n] * pv.x - ci[n] * pv.y, ei = cr[n] * pv.y + ci[n] * pv.x; s += er * bv.x - ei * bv.y; }
;     return s;
; }
; __device__ __forceinline__ void s5_assemble_a(const int TID, const int BID, const Params& p, int l) {
;     const f32x2* pw = (const f32x2*)(p.ws + WS_PW) + l * PWL; const f32x2* bbar = (const f32x2*)(p.ws + WS_BBAR) + l * BBL;
;     float* kmat = (float*)(p.ws + WS_KMAT); bf16_t* pmat = (bf16_t*)(p.ws + WS_PMAT);
;     const float* cre = p.in[10]; const float* cim = p.in[11];
;     const size_t stride = (size_t)gridDim.x * 512;
;     for (size_t idx = (size_t)BID * 512 + TID; idx < (size_t)32 * 2 * 16 * 256; idx += stride) {
;         const int g = (int)(idx >> 13), d = (int)(idx >> 12) & 1, j = (int)(idx >> 8) & 15, c = (int)(idx >> 4) & 15, cp = (int)idx & 15;
;         kmat[idx] = s5_kval(cre, cim, pw, bbar, l, g, d, j, c, cp);
;     }
;     for (size_t idx = (size_t)BID * 512 + TID; idx < (size_t)32 * 256 * 256; idx += stride) {
;         const int g = (int)(idx >> 16), nout = (int)(idx >> 8) & 255, k = (int)idx & 255, d = nout >> 7, ri = (nout >> 6) & 1, n = nout & 63, s = k >> 4, cp = k & 15, j = d == 0 ? 15 - s : s;
;         const f32x2 pv = pw[((size_t)(g * 2 + d) * 17 + j) * 64 + n]; const f32x2 bv = bbar[((size_t)(g * 2 + d) * 64 + n) * 16 + cp];
;         pmat[idx] = f2bf(ri == 0 ? pv.x * bv.x - pv.y * bv.y : pv.x * bv.y + pv.y * bv.x);
	v_pk_mul_f32 v[34:35], v[20:21], v[44:45] op_sel:[1,0] op_sel_hi:[0,0]
	v_pk_fma_f32 v[36:37], v[20:21], v[28:29], v[34:35] neg_lo:[0,0,1] neg_hi:[0,0,1]
	v_pk_fma_f32 v[20:21], v[20:21], v[28:29], v[34:35] op_sel_hi:[1,0,1]
	v_pk_mul_f32 v[34:35], v[22:23], v[44:45] op_sel:[1,1] op_sel_hi:[0,1]
	v_mov_b32_e32 v37, v21
	v_pk_mul_f32 v[20:21], v[32:33], v[36:37]
	v_mov_b32_e32 v32, v29
	v_sub_f32_e32 v20, v20, v21
	v_add_f32_e32 v13, v13, v20
	flat_load_dwordx2 v[20:21], v[58:59] offset:1152
	v_pk_fma_f32 v[32:33], v[22:23], v[32:33], v[34:35] neg_lo:[0,0,1] neg_hi:[0,0,1]
	v_pk_fma_f32 v[22:23], v[22:23], v[28:29], v[34:35] op_sel:[0,1,0]
	s_nop 0
	v_mov_b32_e32 v33, v23
	s_waitcnt vmcnt(0) lgkmcnt(0)
	v_pk_mul_f32 v[20:21], v[20:21], v[32:33]
	s_nop 0
	v_sub_f32_e32 v20, v20, v21
	v_add_f32_e32 v13, v13, v20
	flat_load_dwordx4 v[20:23], v[56:57] offset:80
	flat_load_dwordx2 v[28:29], v[58:59] offset:1280
	s_waitcnt vmcnt(0) lgkmcnt(0)
	v_pk_mul_f32 v[32:33], v[20:21], v[46:47] op_sel:[1,0] op_sel_hi:[0,0]
	v_pk_fma_f32 v[34:35], v[20:21], v[30:31], v[32:33] neg_lo:[0,0,1] neg_hi:[0,0,1]
	v_pk_fma_f32 v[20:21], v[20:21], v[30:31], v[32:33] op_sel_hi:[1,0,1]
	v_mov_b32_e32 v32, v47
	v_mov_b32_e32 v35, v21
	v_pk_mul_f32 v[20:21], v[28:29], v[34:35]
	v_mov_b32_e32 v28, v31
	v_sub_f32_e32 v20, v20, v21
	v_add_f32_e32 v13, v13, v20
	flat_load_dwordx2 v[20:21], v[58:59] offset:1408
	v_mov_b32_e32 v30, v31
	v_pk_mul_f32 v[32:33], v[22:23], v[32:33] op_sel:[1,0] op_sel_hi:[0,0]
	v_pk_fma_f32 v[28:29], v[22:23], v[28:29], v[32:33] neg_lo:[0,0,1] neg_hi:[0,0,1]
	v_pk_fma_f32 v[22:23], v[22:23], v[30:31], v[32:33] op_sel_hi:[1,0,1]
	s_nop 0
	v_mov_b32_e32 v29, v23
	s_waitcnt vmcnt(0) lgkmcnt(0)
	v_pk_mul_f32 v[20:21], v[20:21], v[28:29]
	s_nop 0
	v_sub_f32_e32 v20, v20, v21
	v_add_f32_e32 v13, v13, v20
	flat_load_dwordx4 v[20:23], v[56:57] offset:96
	flat_load_dwordx2 v[28:29], v[58:59] offset:1536
	s_waitcnt vmcnt(0) lgkmcnt(0)
	v_pk_mul_f32 v[30:31], v[20:21], v[40:41] op_sel:[1,0] op_sel_hi:[0,0]
	v_pk_fma_f32 v[32:33], v[20:21], v[24:25], v[30:31] neg_lo:[0,0,1] neg_hi:[0,0,1]
	v_pk_fma_f32 v[20:21], v[20:21], v[24:25], v[30:31] op_sel_hi:[1,0,1]
	v_pk_mul_f32 v[30:31], v[22:23], v[40:41] op_sel:[1,1] op_sel_hi:[0,1]
	v_mov_b32_e32 v33, v21
	v_pk_mul_f32 v[20:21], v[28:29], v[32:33]
	v_mov_b32_e32 v28, v25
	v_sub_f32_e32 v20, v20, v21
	v_add_f32_e32 v13, v13, v20
	flat_load_dwordx2 v[20:21], v[58:59] offset:1664
	v_pk_fma_f32 v[28:29], v[22:23], v[28:29], v[30:31] neg_lo:[0,0,1] neg_hi:[0,0,1]
	v_pk_fma_f32 v[22:23], v[22:23], v[24:25], v[30:31] op_sel:[0,1,0]
	s_nop 0
	v_mov_b32_e32 v29, v23
	s_waitcnt vmcnt(0) lgkmcnt(0)
	v_pk_mul_f32 v[20:21], v[20:21], v[28:29]
	s_nop 0
	v_sub_f32_e32 v20, v20, v21
	v_add_f32_e32 v13, v13, v20
	flat_load_dwordx4 v[20:23], v[56:57] offset:112
	flat_load_dwordx2 v[24:25], v[58:59] offset:1792
	s_waitcnt vmcnt(0) lgkmcnt(0)
	v_pk_mul_f32 v[28:29], v[20:21], v[42:43] op_sel:[1,0] op_sel_hi:[0,0]
	v_pk_fma_f32 v[30:31], v[20:21], v[26:27], v[28:29] neg_lo:[0,0,1] neg_hi:[0,0,1]
	v_pk_fma_f32 v[20:21], v[20:21], v[26:27], v[28:29] op_sel_hi:[1,0,1]
	v_mov_b32_e32 v28, v43
	v_mov_b32_e32 v31, v21
	v_pk_mul_f32 v[20:21], v[24:25], v[30:31]
	v_mov_b32_e32 v24, v27
	v_sub_f32_e32 v20, v20, v21
	v_add_f32_e32 v13, v13, v20
	flat_load_dwordx2 v[20:21], v[58:59] offset:1920
	v_mov_b32_e32 v26, v27
	v_pk_mul_f32 v[28:29], v[22:23], v[28:29] op_sel:[1,0] op_sel_hi:[0,0]
	v_pk_fma_f32 v[24:25], v[22:23], v[24:25], v[28:29] neg_lo:[0,0,1] neg_hi:[0,0,1]
	v_pk_fma_f32 v[22:23], v[22:23], v[26:27], v[28:29] op_sel_hi:[1,0,1]
	s_nop 0
	v_mov_b32_e32 v25, v23
	s_waitcnt vmcnt(0) lgkmcnt(0)
	v_pk_mul_f32 v[20:21], v[20:21], v[24:25]
	s_nop 0
	v_sub_f32_e32 v20, v20, v21
	v_add_f32_e32 v13, v13, v20
	s_cbranch_scc1 .LBB0_1303
	s_mov_b32 s8, s58
	s_mov_b32 s9, s59
	v_lshl_add_u64 v[6:7], v[4:5], 2, s[20:21]
	s_mov_b64 s[38:39], 0x3ffff
	v_lshl_add_u64 v[4:5], v[4:5], 0, s[8:9]
	v_cmp_lt_u64_e32 vcc, s[38:39], v[4:5]
	s_or_b64 s[28:29], vcc, s[28:29]
	flat_store_dword v[6:7], v13
	s_andn2_b64 exec, exec, s[28:29]
	s_cbranch_execnz .LBB0_1302
.LBB0_1305:
	s_or_b64 exec, exec, s[2:3]
	s_mov_b64 s[2:3], 0x200000
	v_cmp_gt_u64_e32 vcc, s[2:3], v[0:1]
	s_and_saveexec_b64 s[2:3], vcc
	s_mov_b32 s10, s58
	s_mov_b32 s40, s60
	s_mov_b32 s11, s59
	s_mov_b32 s41, s61
	s_cbranch_execz .LBB0_1308
	s_add_u32 s8, s94, s88
	s_addc_u32 s9, s95, s89
	s_add_u32 s20, s8, 0x48221000
	s_addc_u32 s21, s9, 0
	s_add_u32 s0, s94, s0
	s_addc_u32 s1, s95, s1
	s_add_u32 s0, s0, 0x48441000
	s_addc_u32 s1, s1, 0
	s_lshl_b64 s[28:29], s[56:57], 10
	s_add_u32 s28, s94, s28
	s_addc_u32 s29, s95, s29
	v_lshl_add_u64 v[2:3], v[194:195], 1, s[28:29]
	s_mov_b64 s[28:29], 0x48e41000
	v_lshl_add_u64 v[2:3], v[2:3], 0, s[28:29]
	s_mov_b64 s[28:29], 0
	v_lshlrev_b32_e32 v4, 3, v12
